# v054 + layers 1..3: workgroups 240..255 run one big Hyena unit at the start of PC (PE queue 16 big units shorter)
# baseline (speedup 1.0000x reference)
_Z6mk_fwd4Args:
	s_mov_b32 s101, 0
	s_load_dwordx4 s[56:59], s[0:1], 0x140
	s_load_dword s82, s[0:1], 0x158
	s_mov_b32 s96, s2
	s_add_u32 s2, s0, 0x158
	s_addc_u32 s3, s1, 0
	v_cmp_gt_u32_e32 vcc, 64, v0
	v_writelane_b32 v250, s2, 0
	s_nop 1
	v_writelane_b32 v250, s3, 1
	s_and_saveexec_b64 s[4:5], vcc
	v_lshl_add_u32 v1, v0, 2, 0
	v_add_u32_e32 v1, 0x22000, v1
	v_mov_b32_e32 v2, 0
	ds_write_b32 v1, v2
	s_or_b64 exec, exec, s[4:5]
	s_load_dwordx2 s[2:3], s[0:1], 0x150
	s_waitcnt lgkmcnt(0)
	s_add_u32 s16, s58, 0x4000
	s_addc_u32 s17, s59, 0
	v_cmp_eq_u32_e32 vcc, 0, v0
	s_sub_i32 s3, s3, s2
	s_cmp_lt_i32 s3, 2
	s_mov_b32 s3, 0
	s_mov_b32 s2, 0
	v_writelane_b32 v250, s3, 2
	s_barrier
	s_cbranch_scc1 .LBB0_7
	s_getreg_b32 s2, hwreg(HW_REG_XCC_ID, 0, 4)
	s_and_b32 s2, s2, 15
	s_and_saveexec_b64 s[4:5], vcc
	s_cbranch_execz .LBB0_6
	s_mov_b64 s[6:7], exec
	v_mbcnt_lo_u32_b32 v1, s6, 0
	v_mbcnt_hi_u32_b32 v1, s7, v1
	v_cmp_eq_u32_e32 vcc, 0, v1
	s_and_b64 s[8:9], exec, vcc
	s_mov_b64 exec, s[8:9]
	s_cbranch_execz .LBB0_6
	s_lshl_b32 s3, s2, 8
	s_bcnt1_i32_b64 s6, s[6:7]
	v_mov_b32_e32 v1, s3
	v_mov_b32_e32 v2, s6
	global_atomic_add v1, v2, s[16:17] offset:1024

.LBB0_891:
	v_readlane_b32 s4, v251, 39
	s_cmp_eq_u32 s4, 0
	s_cbranch_scc1 .Lpc_after_detour
	v_readlane_b32 s4, v251, 36
	s_cmpk_lt_u32 s4, 0xf0
	s_cbranch_scc1 .Lpc_after_detour
	s_mov_b32 s101, 1
	s_branch .LBB0_1346

.LBB0_1346:
	v_readlane_b32 s4, v251, 34
	v_readlane_b32 s5, v251, 35
	v_readlane_b32 s8, v251, 39
	s_mov_b32 s7, s5
	v_readlane_b32 s9, v251, 40
	s_lshl_b32 s6, s8, 7
	v_writelane_b32 v251, s4, 34
	s_nop 1
	v_writelane_b32 v251, s5, 35
	s_lshl_b64 s[4:5], s[6:7], 2
	s_add_u32 s4, s58, s4
	s_addc_u32 s5, s59, s5
	s_add_u32 s4, s4, 0x8100
	s_addc_u32 s5, s5, 0
	v_writelane_b32 v251, s4, 49
	s_nop 1
	v_writelane_b32 v251, s5, 50
	s_nop 0
	v_readlane_b32 s4, v251, 45
	v_readlane_b32 s5, v251, 46
	s_and_b64 s[4:5], s[4:5], exec
	s_movk_i32 s4, 0x308
	s_cselect_b32 s29, s4, 0x508
	s_cmp_lg_u32 s8, 0
	s_cselect_b32 s4, 16, 0
	s_sub_i32 s29, s29, s4
	s_bitcmp0_b32 s8, 0
	s_mov_b32 s4, 0x9300000
	s_cselect_b32 s4, s4, 0x21900000
	s_lshl_b64 s[6:7], s[8:9], 12
	v_writelane_b32 v251, s6, 51
	s_add_u32 s4, s58, s4
	s_nop 0
	v_writelane_b32 v251, s7, 52
	v_writelane_b32 v251, s4, 53
	s_addc_u32 s4, s59, 0
	v_writelane_b32 v251, s4, 54
	s_lshl_b64 s[4:5], s[8:9], 1
	v_writelane_b32 v251, s4, 43
	s_lshl_b64 s[36:37], s[8:9], 10
	s_nop 0
	v_writelane_b32 v251, s5, 44
	s_lshl_b64 s[4:5], s[8:9], 5
	v_writelane_b32 v251, s4, 55
	s_nop 1
	v_writelane_b32 v251, s5, 56
	v_writelane_b32 v251, s29, 57
	s_branch .LBB0_1349
.Lhy_detour:
	s_cmp_eq_u32 s101, 2
	s_cbranch_scc1 .Lhy_return
	s_mov_b32 s101, 2
	v_readlane_b32 s4, v251, 36
	s_addk_i32 s4, 0x108
	v_mov_b32_e32 v2, s4
	s_mov_b64 s[14:15], -1
	s_branch .Lhy_have_ticket
.Lhy_return:
	s_mov_b32 s101, 0
	s_branch .Lpc_after_detour

.LBB0_1349:
	s_cmp_lg_u32 s101, 0
	s_cbranch_scc1 .Lhy_detour
	s_waitcnt lgkmcnt(0)
	s_barrier
	s_mov_b64 s[16:17], exec
	v_readlane_b32 s4, v251, 22
	v_readlane_b32 s5, v251, 23
	s_and_b64 s[4:5], s[16:17], s[4:5]
	s_mov_b64 exec, s[4:5]
	s_cbranch_execz .LBB0_1353
	s_mov_b64 s[26:27], exec
	v_mbcnt_lo_u32_b32 v2, s26, 0
	v_mbcnt_hi_u32_b32 v2, s27, v2
	v_cmp_eq_u32_e32 vcc, 0, v2
	s_and_saveexec_b64 s[14:15], vcc
	s_cbranch_execz .LBB0_1352
	s_bcnt1_i32_b64 s4, s[26:27]
	v_mov_b32_e32 v4, s4
	v_readlane_b32 s4, v251, 49
	v_readlane_b32 s5, v251, 50
	s_nop 4
	global_atomic_add v4, v3, v4, s[4:5] sc0

.Lhy_have_ticket:
	v_cmp_le_i32_e32 vcc, s29, v2
	v_readfirstlane_b32 s9, v2
	s_cbranch_vccnz .LBB0_1348
	s_cmpk_gt_i32 s9, 0x107
	s_cbranch_scc0 .LBB0_1549
	s_cmp_lg_u32 s101, 0
	s_cbranch_scc1 .Lhy_noremap
	v_readlane_b32 s4, v251, 39
	s_cmp_eq_u32 s4, 0
	s_cbranch_scc1 .Lhy_noremap
	s_cmpk_lt_u32 s9, 0x1f8
	s_cbranch_scc1 .Lhy_noremap
	s_add_i32 s9, s9, 16
.Lhy_noremap:
	s_add_i32 s4, s9, 0xfffffef8
	s_and_b32 s5, s4, 0x100
	s_or_b32 s6, s5, 0x4000
	s_lshl_b32 s5, s4, 5
	s_and_b32 s12, s4, 0xff
	s_and_b32 s7, s5, 0x2000
	s_cmpk_lt_u32 s4, 0x200
	s_cselect_b64 s[18:19], -1, 0
	s_and_b64 s[4:5], s[18:19], exec
	s_movk_i32 s4, 0x2000
	s_cselect_b32 s52, s4, 0x100
	s_mul_i32 s4, s12, 0x8400
	v_mov_b32_e32 v59, v0
	v_writelane_b32 v251, s9, 58
	s_cselect_b32 s6, s7, s6
	s_lshl_b32 s4, s4, 1
	v_readlane_b32 s8, v252, 43
	v_readlane_b32 s9, v252, 44
	v_writelane_b32 v251, s4, 59
	s_add_u32 s7, s8, s4
	s_load_dwordx2 s[4:5], s[0:1], 0x98
	s_addc_u32 s8, s9, 0
	s_lshl_b32 s6, s6, 1
	v_writelane_b32 v251, s6, 60
	s_add_u32 s16, s7, s6
	v_readlane_b32 s10, v251, 39
	s_addc_u32 s17, s8, 0
	s_mul_i32 s6, s10, 0x4800
	s_waitcnt lgkmcnt(0)
	s_add_u32 s4, s4, s6
	s_load_dwordx2 s[6:7], s[0:1], 0xa0
	s_mul_hi_u32 s8, s10, 0x4800
	s_addc_u32 s5, s5, s8
	s_lshl_b32 s8, s12, 3
	s_add_u32 s44, s4, s8
	s_addc_u32 s45, s5, 0
	s_mul_i32 s4, s10, 0x1800
	s_waitcnt lgkmcnt(0)
	s_add_u32 s4, s6, s4
	s_mul_hi_u32 s5, s10, 0x1800
	v_mov_b32_e32 v2, s44
	s_addc_u32 s5, s7, s5
	v_add_co_u32_e32 v6, vcc, 0x1000, v2
	v_mov_b32_e32 v9, s45
	s_add_u32 s26, s4, s8
	v_addc_co_u32_e32 v7, vcc, 0, v9, vcc
	s_addc_u32 s27, s5, 0
	v_mov_b64_e32 v[4:5], s[44:45]
	v_add_co_u32_e32 v8, vcc, 0x3000, v2
	v_lshlrev_b32_e32 v52, 3, v59
	s_nop 0
	v_addc_co_u32_e32 v9, vcc, 0, v9, vcc
	flat_load_dword v89, v[4:5]
	flat_load_dword v83, v[6:7] offset:2048
	flat_load_dword v85, v[8:9]
	v_mov_b64_e32 v[4:5], s[26:27]
	flat_load_dword v87, v[4:5]
	v_cmp_gt_i32_e64 s[34:35], s52, v52
	v_mov_b32_e32 v64, 0
	v_mov_b32_e32 v43, 0
	v_ashrrev_i32_e32 v53, 31, v52
	v_mov_b32_e32 v42, 0
	v_mov_b32_e32 v41, 0
	v_mov_b32_e32 v40, 0
	v_mov_b32_e32 v65, 0
	v_readlane_b32 s11, v251, 40
	s_and_saveexec_b64 s[38:39], s[34:35]
	s_cbranch_execz .LBB0_1361
	v_lshl_add_u64 v[4:5], v[52:53], 1, s[16:17]
	global_load_dwordx4 v[40:43], v[4:5], off
	v_cmp_lt_i32_e32 vcc, 0, v52
	v_mov_b32_e32 v65, 0
	v_mov_b32_e32 v64, 0
	s_and_saveexec_b64 s[14:15], vcc
	s_cbranch_execz .LBB0_1358
	v_mov_b32_e32 v2, v52
	v_lshl_add_u64 v[6:7], v[2:3], 1, s[16:17]
	global_load_ushort v64, v[6:7], off offset:-2
